# static priority for waves 4-7 also in the GLU fp8 K-loop (per-block s_setprio flips removed), on top of the out-proj change
# baseline (speedup 1.0000x reference)
;     __device__ __forceinline__ bool next(int i, Unit& u) const { if (i) return false; u.pm = pm; u.pn = pn; return true; }
; #define PG8_STAGE(bufoff, goff, voff) do { _Pragma("unroll") for (int _i = 0; _i < 2; ++_i) \
;         __builtin_amdgcn_raw_ptr_buffer_load_lds(R_##voff, (LAS void*)(lds + (bufoff) + ldsw + _i * 8192), 16, (int)(voff)[_i], (int)(goff), 0, 0); } while (0)
; #define PG8_WAIT_V(n) asm volatile("s_waitcnt vmcnt(" #n ")" ::: "memory")
; #define PG8_BAR __builtin_amdgcn_s_barrier()
; template <class Epi, class Sched, bool ALIGN_EPI, bool SP2>
; __device__ __forceinline__ void gemm_phase(LAS unsigned char* lds, const Gemm g, const Sched& S, const Epi& E, int tid_in) {
;     ...
;     for (;;) {
;         const bool has_next = S.next(ui + 1, nxt);
;         const unsigned nA = has_next ? (unsigned)nxt.pm * tstepA : cA, nB = has_next ? (unsigned)nxt.pn * tstepB : cB;
;         for (int t = 0; t < nt; t += 2) {
;             const bool last = (t == nt - 2);
;             const unsigned a1 = cA + (unsigned)(t + 1) * kstep;
;             const unsigned a2 = last ? nA : cA + (unsigned)(t + 2) * kstep, b2 = last ? nB : cB + (unsigned)(t + 2) * kstep;
;             const unsigned a3 = a2 + kstep, b3 = b2 + kstep;
;             if constexpr (Epi::MIDK) { if (t == g.kmid) E.midk(acc, wr, fr); }
;             if constexpr (SP2) {
;             PG8_LDB(B0, 0, 0); PG8_LDB(B1, 0, 1); PG8_SCHED; PG8_LDA(At, 0, 0); PG8_STAGE(PG8_SA(1, 1), a1 + hstepA, voffA);
;             PG8_WAIT_V(8); PG8_WAIT_L(0); PG8_BAR; PG8_MMA(0, 0, At, B0); PG8_MMA(0, 1, At, B1); PG8_BAR; PG8_SCHED;
;             PG8_LDA(At, 0, 1); PG8_STAGE(PG8_SB(0, 0), b2, voffB); PG8_STAGE(PG8_SB(0, 1), b2 + hstepB, voffB); PG8_STAGE(PG8_SA(0, 0), a2, voffA);
;             PG8_WAIT_V(8); PG8_WAIT_L(0); PG8_BAR; PG8_MMA(1, 0, At, B0); PG8_MMA(1, 1, At, B1); PG8_BAR; PG8_SCHED;
;             PG8_LDB(B0, 1, 0); PG8_LDB(B1, 1, 1); PG8_SCHED; PG8_LDA(At, 1, 0); PG8_STAGE(PG8_SA(0, 1), a2 + hstepA, voffA);
;             PG8_WAIT_V(8); PG8_WAIT_L(0); PG8_BAR; PG8_MMA(0, 0, At, B0); PG8_MMA(0, 1, At, B1); PG8_BAR; PG8_SCHED;
;             PG8_LDA(At, 1, 1); PG8_STAGE(PG8_SB(1, 0), b3, voffB); PG8_STAGE(PG8_SB(1, 1), b3 + hstepB, voffB); PG8_STAGE(PG8_SA(1, 0), a3, voffA);
;             PG8_WAIT_V(8); PG8_WAIT_L(0); PG8_BAR; PG8_MMA(1, 0, At, B0); PG8_MMA(1, 1, At, B1); PG8_BAR; PG8_SCHED;
.LBB0_97:
	s_lshl_b32 s78, s77, 19
	s_and_b64 s[2:3], s[36:37], exec
	s_cselect_b32 s2, s78, s19
	s_lshl_b32 s79, s76, 19
	s_and_b64 s[14:15], s[36:37], exec
	v_mov_b32_e32 v2, 0
	v_mov_b32_e32 v243, 0x3e4ccccd
	v_mov_b32_e32 v236, 0x358637bd
	s_cselect_b32 s3, s79, s17
	s_add_i32 s16, s19, 0x40080
	s_addk_i32 s17, 0x100
	s_mov_b32 s19, -2
	v_mov_b32_e32 v3, v2
	v_mov_b32_e32 v4, v2
	v_mov_b32_e32 v5, v2
	v_mov_b32_e32 v6, v2
	v_mov_b32_e32 v7, v2
	v_mov_b32_e32 v8, v2
	v_mov_b32_e32 v9, v2
	s_waitcnt vmcnt(17)
	v_mov_b32_e32 v18, v2
	v_mov_b32_e32 v19, v2
	v_mov_b32_e32 v20, v2
	v_mov_b32_e32 v21, v2
	s_waitcnt vmcnt(16)
	v_mov_b32_e32 v22, v2
	v_mov_b32_e32 v23, v2
	v_mov_b32_e32 v24, v2
	v_mov_b32_e32 v25, v2
	s_waitcnt vmcnt(15)
	v_mov_b32_e32 v34, v2
	v_mov_b32_e32 v35, v2
	v_mov_b32_e32 v36, v2
	v_mov_b32_e32 v37, v2
	s_waitcnt vmcnt(14)
	v_mov_b32_e32 v38, v2
	v_mov_b32_e32 v39, v2
	v_mov_b32_e32 v40, v2
	v_mov_b32_e32 v41, v2
	v_mov_b32_e32 v58, v2
	v_mov_b32_e32 v59, v2
	v_mov_b32_e32 v60, v2
	v_mov_b32_e32 v61, v2
	v_mov_b32_e32 v62, v2
	v_mov_b32_e32 v63, v2
	v_mov_b32_e32 v64, v2
	v_mov_b32_e32 v65, v2
	v_mov_b32_e32 v10, v2
	v_mov_b32_e32 v11, v2
	v_mov_b32_e32 v12, v2
	v_mov_b32_e32 v13, v2
	v_mov_b32_e32 v14, v2
	v_mov_b32_e32 v15, v2
	v_mov_b32_e32 v16, v2
	v_mov_b32_e32 v17, v2
	v_mov_b32_e32 v26, v2
	v_mov_b32_e32 v27, v2
	v_mov_b32_e32 v28, v2
	v_mov_b32_e32 v29, v2
	v_mov_b32_e32 v30, v2
	v_mov_b32_e32 v31, v2
	v_mov_b32_e32 v32, v2
	v_mov_b32_e32 v33, v2
	v_mov_b32_e32 v42, v2
	v_mov_b32_e32 v43, v2
	v_mov_b32_e32 v44, v2
	v_mov_b32_e32 v45, v2
	v_mov_b32_e32 v46, v2
	v_mov_b32_e32 v47, v2
	v_mov_b32_e32 v48, v2
	v_mov_b32_e32 v49, v2
	v_mov_b32_e32 v74, v2
	v_mov_b32_e32 v75, v2
	v_mov_b32_e32 v76, v2
	v_mov_b32_e32 v77, v2
	v_mov_b32_e32 v78, v2
	v_mov_b32_e32 v79, v2
	v_mov_b32_e32 v80, v2
	v_mov_b32_e32 v81, v2
	v_mov_b32_e32 v82, v2
	v_mov_b32_e32 v83, v2
	v_mov_b32_e32 v84, v2
	v_mov_b32_e32 v85, v2
	v_mov_b32_e32 v86, v2
	v_mov_b32_e32 v87, v2
	v_mov_b32_e32 v88, v2
	v_mov_b32_e32 v89, v2
	v_mov_b32_e32 v98, v2
	v_mov_b32_e32 v99, v2
	v_mov_b32_e32 v100, v2
	v_mov_b32_e32 v101, v2
	v_mov_b32_e32 v102, v2
	v_mov_b32_e32 v103, v2
	v_mov_b32_e32 v104, v2
	v_mov_b32_e32 v105, v2
	v_mov_b32_e32 v116, v2
	v_mov_b32_e32 v117, v2
	v_mov_b32_e32 v118, v2
	v_mov_b32_e32 v119, v2
	v_mov_b32_e32 v120, v2
	v_mov_b32_e32 v121, v2
	v_mov_b32_e32 v122, v2
	v_mov_b32_e32 v123, v2
	v_mov_b32_e32 v140, v2
	v_mov_b32_e32 v141, v2
	v_mov_b32_e32 v142, v2
	v_mov_b32_e32 v143, v2
	v_mov_b32_e32 v144, v2
	v_mov_b32_e32 v145, v2
	v_mov_b32_e32 v146, v2
	v_mov_b32_e32 v147, v2
	v_mov_b32_e32 v90, v2
	v_mov_b32_e32 v91, v2
	v_mov_b32_e32 v92, v2
	v_mov_b32_e32 v93, v2
	v_mov_b32_e32 v94, v2
	v_mov_b32_e32 v95, v2
	v_mov_b32_e32 v96, v2
	v_mov_b32_e32 v97, v2
	v_mov_b32_e32 v106, v2
	v_mov_b32_e32 v107, v2
	v_mov_b32_e32 v108, v2
	v_mov_b32_e32 v109, v2
	v_mov_b32_e32 v110, v2
	v_mov_b32_e32 v111, v2
	v_mov_b32_e32 v112, v2
	v_mov_b32_e32 v113, v2
	v_mov_b32_e32 v124, v2
	v_mov_b32_e32 v125, v2
	v_mov_b32_e32 v126, v2
	v_mov_b32_e32 v127, v2
	v_mov_b32_e32 v128, v2
	v_mov_b32_e32 v129, v2
	v_mov_b32_e32 v130, v2
	v_mov_b32_e32 v131, v2
	v_mov_b32_e32 v172, v2
	v_mov_b32_e32 v173, v2
	v_mov_b32_e32 v174, v2
	v_mov_b32_e32 v175, v2
	v_mov_b32_e32 v176, v2
	v_mov_b32_e32 v177, v2
	v_mov_b32_e32 v178, v2
	v_mov_b32_e32 v179, v2
	s_and_b64 vcc, exec, s[56:57]
	s_cbranch_vccnz .Lpr_skip98
	s_setprio 1
.Lpr_skip98:
.LBB0_98:
	v_add_u32_e32 v70, 0x10000, v241
	v_add_u32_e32 v152, 0x14000, v241
	ds_read_b128 v[50:53], v70
	ds_read_b128 v[54:57], v70 offset:1024
	ds_read_b128 v[66:69], v70 offset:2048
	ds_read_b128 v[70:73], v70 offset:3072
	ds_read_b128 v[132:135], v152
	ds_read_b128 v[136:139], v152 offset:1024
	ds_read_b128 v[148:151], v152 offset:2048
	ds_read_b128 v[152:155], v152 offset:3072
	s_add_i32 s14, s16, 0xfffc0080
	s_cmp_eq_u32 s19, 12
	s_cselect_b32 s27, s2, s14
	s_cselect_b32 s25, s3, s17
	s_or_b32 s20, s27, 0x80
	s_mov_b32 m0, s71
	ds_read_b128 v[156:159], v242
	ds_read_b128 v[160:163], v242 offset:1024
	ds_read_b128 v[164:167], v242 offset:2048
	ds_read_b128 v[168:171], v242 offset:3072
	ds_read_b128 v[180:183], v242 offset:4096
	ds_read_b128 v[184:187], v242 offset:5120
	ds_read_b128 v[188:191], v242 offset:6144
	ds_read_b128 v[192:195], v242 offset:7168
	buffer_load_dwordx4 v0, s[84:87], s16 offen lds
	s_mov_b32 m0, s73
	s_nop 0
	buffer_load_dwordx4 v237, s[84:87], s16 offen lds
	s_waitcnt vmcnt(8)
	s_waitcnt lgkmcnt(0)
	s_barrier
	s_waitcnt lgkmcnt(6)
	v_mfma_f32_16x16x128_f8f6f4 v[176:179], v[50:57], v[156:163], v[176:179]
	v_mfma_f32_16x16x128_f8f6f4 v[172:175], v[66:73], v[156:163], v[172:175]
	s_waitcnt lgkmcnt(4)
	v_mfma_f32_16x16x128_f8f6f4 v[128:131], v[50:57], v[164:171], v[128:131]
	v_mfma_f32_16x16x128_f8f6f4 v[124:127], v[66:73], v[164:171], v[124:127]
	s_waitcnt lgkmcnt(2)
	v_mfma_f32_16x16x128_f8f6f4 v[196:199], v[50:57], v[180:187], v[110:113]
	v_mfma_f32_16x16x128_f8f6f4 v[200:203], v[66:73], v[180:187], v[106:109]
	s_waitcnt lgkmcnt(0)
	v_mfma_f32_16x16x128_f8f6f4 v[204:207], v[50:57], v[188:195], v[94:97]
	v_mfma_f32_16x16x128_f8f6f4 v[208:211], v[66:73], v[188:195], v[90:93]
	v_mfma_f32_16x16x128_f8f6f4 v[144:147], v[132:139], v[156:163], v[144:147]
	v_mfma_f32_16x16x128_f8f6f4 v[140:143], v[148:155], v[156:163], v[140:143]
	v_mfma_f32_16x16x128_f8f6f4 v[120:123], v[132:139], v[164:171], v[120:123]
	v_mfma_f32_16x16x128_f8f6f4 v[116:119], v[148:155], v[164:171], v[116:119]
	v_mfma_f32_16x16x128_f8f6f4 v[156:159], v[132:139], v[180:187], v[102:105]
	v_mfma_f32_16x16x128_f8f6f4 v[160:163], v[148:155], v[180:187], v[98:101]
	v_mfma_f32_16x16x128_f8f6f4 v[164:167], v[132:139], v[188:195], v[86:89]
	v_mfma_f32_16x16x128_f8f6f4 v[168:171], v[148:155], v[188:195], v[82:85]
	s_barrier
; #define PG8_STAGE(bufoff, goff, voff) do { _Pragma("unroll") for (int _i = 0; _i < 2; ++_i) \
;         __builtin_amdgcn_raw_ptr_buffer_load_lds(R_##voff, (LAS void*)(lds + (bufoff) + ldsw + _i * 8192), 16, (int)(voff)[_i], (int)(goff), 0, 0); } while (0)
; #define PG8_WAIT_V(n) asm volatile("s_waitcnt vmcnt(" #n ")" ::: "memory")
; #define PG8_WAIT_L(n) asm volatile("s_waitcnt lgkmcnt(" #n ")" ::: "memory")
; #define PG8_BAR __builtin_amdgcn_s_barrier()
; #define PG8_SCHED __builtin_amdgcn_sched_barrier(0)
; template <class Epi, class Sched, bool ALIGN_EPI, bool SP2>
; __device__ __forceinline__ void gemm_phase(LAS unsigned char* lds, const Gemm g, const Sched& S, const Epi& E, int tid_in) {
;     ...
;             PG8_LDB(B0, 0, 0); PG8_LDB(B1, 0, 1); PG8_SCHED; PG8_LDA(At, 0, 0); PG8_STAGE(PG8_SA(1, 1), a1 + hstepA, voffA);
;             PG8_WAIT_V(8); PG8_WAIT_L(0); PG8_BAR; PG8_MMA(0, 0, At, B0); PG8_MMA(0, 1, At, B1); PG8_BAR; PG8_SCHED;
;             PG8_LDA(At, 0, 1); PG8_STAGE(PG8_SB(0, 0), b2, voffB); PG8_STAGE(PG8_SB(0, 1), b2 + hstepB, voffB); PG8_STAGE(PG8_SA(0, 0), a2, voffA);
;             PG8_WAIT_V(8); PG8_WAIT_L(0); PG8_BAR; PG8_MMA(1, 0, At, B0); PG8_MMA(1, 1, At, B1); PG8_BAR; PG8_SCHED;
;             PG8_LDB(B0, 1, 0); PG8_LDB(B1, 1, 1); PG8_SCHED; PG8_LDA(At, 1, 0); PG8_STAGE(PG8_SA(0, 1), a2 + hstepA, voffA);
;             PG8_WAIT_V(8); PG8_WAIT_L(0); PG8_BAR; PG8_MMA(0, 0, At, B0); PG8_MMA(0, 1, At, B1); PG8_BAR; PG8_SCHED;
;             PG8_LDA(At, 1, 1); PG8_STAGE(PG8_SB(1, 0), b3, voffB); PG8_STAGE(PG8_SB(1, 1), b3 + hstepB, voffB); PG8_STAGE(PG8_SA(1, 0), a3, voffA);
;             PG8_WAIT_V(8); PG8_WAIT_L(0); PG8_BAR; PG8_MMA(1, 0, At, B0); PG8_MMA(1, 1, At, B1); PG8_BAR; PG8_SCHED;
	s_mov_b32 m0, s12
	s_mov_b32 s42, s86
	s_mov_b32 s43, s87
	s_nop 1
	ds_read_b128 v[82:85], v242 offset:16384
	ds_read_b128 v[86:89], v242 offset:17408
	ds_read_b128 v[90:93], v242 offset:18432
	ds_read_b128 v[94:97], v242 offset:19456
	ds_read_b128 v[98:101], v242 offset:20480
	ds_read_b128 v[102:105], v242 offset:21504
	ds_read_b128 v[106:109], v242 offset:22528
	ds_read_b128 v[110:113], v242 offset:23552
	buffer_load_dwordx4 v115, s[40:43], s25 offen lds
	s_mov_b32 m0, s13
	s_add_i32 s14, s25, 0x10000
	buffer_load_dwordx4 v238, s[40:43], s25 offen lds
	s_mov_b32 m0, s53
	s_nop 0
	buffer_load_dwordx4 v115, s[40:43], s14 offen lds
	s_mov_b32 m0, s58
	s_nop 0
	buffer_load_dwordx4 v238, s[40:43], s14 offen lds
	s_mov_b32 m0, s9
	s_nop 0
	buffer_load_dwordx4 v0, s[84:87], s27 offen lds
	s_mov_b32 m0, s59
	s_nop 0
	buffer_load_dwordx4 v237, s[84:87], s27 offen lds
	s_waitcnt vmcnt(8)
	s_waitcnt lgkmcnt(0)
	s_barrier
	s_waitcnt lgkmcnt(6)
	v_mfma_f32_16x16x128_f8f6f4 v[78:81], v[50:57], v[82:89], v[78:81]
	v_mfma_f32_16x16x128_f8f6f4 v[74:77], v[66:73], v[82:89], v[74:77]
	s_waitcnt lgkmcnt(4)
	v_mfma_f32_16x16x128_f8f6f4 v[180:183], v[50:57], v[90:97], v[46:49]
	v_mfma_f32_16x16x128_f8f6f4 v[184:187], v[66:73], v[90:97], v[42:45]
	s_waitcnt lgkmcnt(2)
	v_mfma_f32_16x16x128_f8f6f4 v[188:191], v[50:57], v[98:105], v[30:33]
	v_mfma_f32_16x16x128_f8f6f4 v[192:195], v[66:73], v[98:105], v[26:29]
	s_waitcnt lgkmcnt(0)
	v_mfma_f32_16x16x128_f8f6f4 v[212:215], v[50:57], v[106:113], v[14:17]
	v_mfma_f32_16x16x128_f8f6f4 v[216:219], v[66:73], v[106:113], v[10:13]
	v_mfma_f32_16x16x128_f8f6f4 v[62:65], v[132:139], v[82:89], v[62:65]
	v_mfma_f32_16x16x128_f8f6f4 v[58:61], v[148:155], v[82:89], v[58:61]
	v_mfma_f32_16x16x128_f8f6f4 v[220:223], v[132:139], v[90:97], v[38:41]
	v_mfma_f32_16x16x128_f8f6f4 v[224:227], v[148:155], v[90:97], v[34:37]
	v_mfma_f32_16x16x128_f8f6f4 v[228:231], v[132:139], v[98:105], v[22:25]
	v_mfma_f32_16x16x128_f8f6f4 v[244:247], v[148:155], v[98:105], v[18:21]
	v_mfma_f32_16x16x128_f8f6f4 v[248:251], v[132:139], v[106:113], v[6:9]
	v_mfma_f32_16x16x128_f8f6f4 v[232:235], v[148:155], v[106:113], v[2:5]
	s_barrier
	v_add_u32_e32 v10, 0x18000, v241
	s_nop 3
	ds_read_b128 v[2:5], v10
	ds_read_b128 v[6:9], v10 offset:1024
	ds_read_b128 v[18:21], v10 offset:2048
	ds_read_b128 v[22:25], v10 offset:3072
	v_add_u32_e32 v10, 0x1c000, v241
	ds_read_b128 v[50:53], v10
	ds_read_b128 v[54:57], v10 offset:1024
	ds_read_b128 v[66:69], v10 offset:2048
	ds_read_b128 v[70:73], v10 offset:3072
	s_add_i32 s27, s27, 0x40000
	s_mov_b32 m0, s60
	ds_read_b128 v[10:13], v242 offset:32768
	ds_read_b128 v[14:17], v242 offset:33792
	ds_read_b128 v[26:29], v242 offset:34816
	ds_read_b128 v[30:33], v242 offset:35840
	ds_read_b128 v[34:37], v242 offset:36864
	ds_read_b128 v[38:41], v242 offset:37888
	ds_read_b128 v[42:45], v242 offset:38912
	ds_read_b128 v[46:49], v242 offset:39936
	buffer_load_dwordx4 v0, s[84:87], s27 offen lds
	s_mov_b32 m0, s61
	s_nop 0
	buffer_load_dwordx4 v237, s[84:87], s27 offen lds
	s_waitcnt vmcnt(8)
	s_waitcnt lgkmcnt(0)
	s_barrier
	s_waitcnt lgkmcnt(6)
	v_mfma_f32_16x16x128_f8f6f4 v[176:179], v[2:9], v[10:17], v[176:179]
	v_mfma_f32_16x16x128_f8f6f4 v[172:175], v[18:25], v[10:17], v[172:175]
	s_waitcnt lgkmcnt(4)
	v_mfma_f32_16x16x128_f8f6f4 v[128:131], v[2:9], v[26:33], v[128:131]
	v_mfma_f32_16x16x128_f8f6f4 v[124:127], v[18:25], v[26:33], v[124:127]
	s_waitcnt lgkmcnt(2)
	v_mfma_f32_16x16x128_f8f6f4 v[110:113], v[2:9], v[34:41], v[196:199]
	v_mfma_f32_16x16x128_f8f6f4 v[106:109], v[18:25], v[34:41], v[200:203]
	s_waitcnt lgkmcnt(0)
	v_mfma_f32_16x16x128_f8f6f4 v[94:97], v[2:9], v[42:49], v[204:207]
	v_mfma_f32_16x16x128_f8f6f4 v[90:93], v[18:25], v[42:49], v[208:211]
	v_mfma_f32_16x16x128_f8f6f4 v[144:147], v[50:57], v[10:17], v[144:147]
	v_mfma_f32_16x16x128_f8f6f4 v[140:143], v[66:73], v[10:17], v[140:143]
	v_mfma_f32_16x16x128_f8f6f4 v[120:123], v[50:57], v[26:33], v[120:123]
	v_mfma_f32_16x16x128_f8f6f4 v[116:119], v[66:73], v[26:33], v[116:119]
	v_mfma_f32_16x16x128_f8f6f4 v[102:105], v[50:57], v[34:41], v[156:159]
	v_mfma_f32_16x16x128_f8f6f4 v[98:101], v[66:73], v[34:41], v[160:163]
	v_mfma_f32_16x16x128_f8f6f4 v[86:89], v[50:57], v[42:49], v[164:167]
	v_mfma_f32_16x16x128_f8f6f4 v[82:85], v[66:73], v[42:49], v[168:171]
	s_barrier
	s_mov_b32 m0, s49
	s_or_b32 s14, s25, 0x80
	ds_read_b128 v[34:37], v242 offset:49152
	ds_read_b128 v[38:41], v242 offset:50176
	ds_read_b128 v[132:135], v242 offset:51200
	ds_read_b128 v[136:139], v242 offset:52224
	ds_read_b128 v[148:151], v242 offset:53248
	ds_read_b128 v[152:155], v242 offset:54272
	ds_read_b128 v[156:159], v242 offset:55296
	ds_read_b128 v[160:163], v242 offset:56320
	buffer_load_dwordx4 v115, s[40:43], s14 offen lds
	s_mov_b32 m0, s31
	s_add_i32 s25, s25, 0x10080
	buffer_load_dwordx4 v238, s[40:43], s14 offen lds
	s_mov_b32 m0, s67
	s_nop 0
	buffer_load_dwordx4 v115, s[40:43], s25 offen lds
	s_mov_b32 m0, s68
	s_nop 0
	buffer_load_dwordx4 v238, s[40:43], s25 offen lds
	s_mov_b32 m0, s30
	s_nop 0
	buffer_load_dwordx4 v0, s[84:87], s20 offen lds
	s_mov_b32 m0, s66
	s_nop 0
	buffer_load_dwordx4 v237, s[84:87], s20 offen lds
	s_waitcnt vmcnt(8)
	s_waitcnt lgkmcnt(0)
	s_barrier
	s_waitcnt lgkmcnt(6)
	v_mfma_f32_16x16x128_f8f6f4 v[78:81], v[2:9], v[34:41], v[78:81]
	v_mfma_f32_16x16x128_f8f6f4 v[74:77], v[18:25], v[34:41], v[74:77]
	s_waitcnt lgkmcnt(4)
	v_mfma_f32_16x16x128_f8f6f4 v[46:49], v[2:9], v[132:139], v[180:183]
	v_mfma_f32_16x16x128_f8f6f4 v[42:45], v[18:25], v[132:139], v[184:187]
	s_waitcnt lgkmcnt(2)
	v_mfma_f32_16x16x128_f8f6f4 v[30:33], v[2:9], v[148:155], v[188:191]
	v_mfma_f32_16x16x128_f8f6f4 v[26:29], v[18:25], v[148:155], v[192:195]
	s_waitcnt lgkmcnt(0)
	v_mfma_f32_16x16x128_f8f6f4 v[14:17], v[2:9], v[156:163], v[212:215]
	v_mfma_f32_16x16x128_f8f6f4 v[10:13], v[18:25], v[156:163], v[216:219]
	v_mfma_f32_16x16x128_f8f6f4 v[62:65], v[50:57], v[34:41], v[62:65]
	v_mfma_f32_16x16x128_f8f6f4 v[58:61], v[66:73], v[34:41], v[58:61]
	v_mfma_f32_16x16x128_f8f6f4 v[38:41], v[50:57], v[132:139], v[220:223]
	v_mfma_f32_16x16x128_f8f6f4 v[34:37], v[66:73], v[132:139], v[224:227]
	v_mfma_f32_16x16x128_f8f6f4 v[22:25], v[50:57], v[148:155], v[228:231]
	v_mfma_f32_16x16x128_f8f6f4 v[18:21], v[66:73], v[148:155], v[244:247]
	v_mfma_f32_16x16x128_f8f6f4 v[6:9], v[50:57], v[156:163], v[248:251]
	v_mfma_f32_16x16x128_f8f6f4 v[2:5], v[66:73], v[156:163], v[232:235]
	s_barrier
	s_add_i32 s19, s19, 2
	s_addk_i32 s16, 0x100
	s_addk_i32 s17, 0x100
	s_cmp_gt_u32 s19, 13
	s_cbranch_scc0 .LBB0_98
	s_setprio 0
	s_and_b64 vcc, exec, s[56:57]
	s_cbranch_vccz .LBB0_101
	s_barrier
